# b14 + CMP2 counted wait (row store stays in flight)
# baseline (speedup 1.0000x reference)
.LBB0_1197:
	s_or_b64 exec, exec, s[0:1]
	v_lshrrev_b32_e32 v4, 6, v188
	v_lshl_add_u32 v0, s33, 3, v4
	s_mov_b32 s10, 0x8000
	v_cmp_gt_i32_e32 vcc, s10, v0
	s_waitcnt lgkmcnt(0)
	s_barrier
	s_and_saveexec_b64 s[4:5], vcc
	s_cbranch_execz .LBB0_1204
	s_add_i32 s6, 0, 0x10000
	s_add_u32 s0, s44, 0x36040000
	v_ashrrev_i32_e32 v1, 31, v0
	s_addc_u32 s1, s45, 0
	v_and_b32_e32 v8, 63, v188
	v_lshlrev_b64 v[2:3], 9, v[0:1]
	v_lshl_add_u64 v[6:7], s[0:1], 0, v[2:3]
	v_lshlrev_b32_e32 v2, 2, v8
	v_mov_b32_e32 v3, 0
	v_lshl_add_u64 v[6:7], v[6:7], 0, v[2:3]
	global_load_dword v9, v[6:7], off
	global_load_dword v12, v[6:7], off offset:256
	v_lshlrev_b32_e32 v6, 1, v8
	v_mov_b32_e32 v7, v3
	v_lshlrev_b32_e32 v10, 9, v4
	v_lshl_add_u64 v[4:5], s[0:1], 0, v[2:3]
	v_lshl_add_u64 v[6:7], s[44:45], 0, v[6:7]
	s_mov_b64 s[0:1], 0x35c40000
	v_add3_u32 v11, s6, v10, v2
	s_lshl_b32 s11, s66, 3
	v_lshl_add_u64 v[6:7], v[6:7], 0, s[0:1]
	s_mov_b64 s[6:7], 0
	s_movk_i32 s12, 0x7fff
	s_movk_i32 s13, 0x8000
	s_movk_i32 s14, 0x1fc
	s_waitcnt vmcnt(0)
.LBB0_1199:
	v_add_u32_e32 v8, s11, v0
	v_cmp_gt_i32_e64 s[0:1], s10, v8
	v_cmp_lt_i32_e32 vcc, s12, v8
	s_waitcnt vmcnt(1)
	ds_write2st64_b32 v11, v9, v12 offset1:1
	s_and_saveexec_b64 s[8:9], s[0:1]
	s_cbranch_execz .LBB0_1201
	v_ashrrev_i32_e32 v9, 31, v8
	v_lshlrev_b64 v[12:13], 9, v[8:9]
	v_lshl_add_u64 v[14:15], v[4:5], 0, v[12:13]
	global_load_dword v9, v[14:15], off
	global_load_dword v12, v[14:15], off offset:256
